# mixed round: the wait for the deferred tiles moved to just before a unit's first store, polled at most once per wave
# speedup vs baseline: 1.0004x; 1.0004x over previous
; #define TILE_MN(t, M0, N0) do { int pan_ = (t) / (mtiles * 8); if (pan_ >= npan) pan_ = npan - 1; const int pw_ = (pan_ == npan - 1) ? ntiles - 8 * pan_ : 8; const int loc_ = (t) - pan_ * mtiles * 8; \
;         M0 = (loc_ / pw_) * 128; N0 = (8 * pan_ + loc_ % pw_) * 128; } while (0)
; template <class Epi>
; DI void gemm_phase(const u16* __restrict__ A, const u16* __restrict__ B, int mtiles, int ntiles, char* lds, const Epi& epi) {
;     const int ntile = mtiles * ntiles;
;     const int vb = (blockIdx.x & 7) * (gridDim.x >> 3) + (blockIdx.x >> 3);
;     const int npan = ntiles >> 3;
;     int tile = vb; if (tile >= ntile) return;
;     ...
;     int m0, n0; TILE_MN(tile, m0, n0);
.LBB0_94:
	s_mov_b32 s100, 0
	v_writelane_b32 v237, 0, 7
	v_writelane_b32 v236, s39, 4
	s_or_b64 exec, exec, s[4:5]
	s_waitcnt lgkmcnt(0)
	s_barrier
	s_load_dword s95, s[0:1], 0xc8
	s_and_b32 s4, s33, 7
	s_add_u32 s0, s0, 0xc8
	s_addc_u32 s1, s1, 0
	v_writelane_b32 v236, s0, 5
	s_nop 1
	v_writelane_b32 v236, s1, 6
	s_waitcnt lgkmcnt(0)
	s_lshr_b32 s0, s95, 3
	s_mul_i32 s0, s0, s4
	s_lshr_b32 s1, s33, 3
	s_add_i32 s0, s0, s1
	v_writelane_b32 v236, s0, 7
	s_cmpk_gt_i32 s0, 0x1103
	v_writelane_b32 v236, s95, 8
	s_cbranch_scc1 .LBB0_144
	v_readlane_b32 s33, v236, 7
	s_mov_b32 s96, s33
	s_cmpk_lt_i32 s33, 0xe97
	s_cbranch_scc1 .Lrm_done_m0
	s_cmpk_lt_i32 s33, 0x1000
	s_cbranch_scc0 .Lrm_def_m0
	s_add_i32 s96, s33, 0x104
	s_cmpk_lt_i32 s33, 0xfdc
	s_cbranch_scc0 .Lrm_done_m0
	s_sub_i32 s97, s33, 0xe97
	s_mul_i32 s97, s97, 0x3334
	s_lshr_b32 s97, s97, 16
	s_lshl_b32 s97, s97, 2
	s_add_i32 s96, s33, s97
	s_branch .Lrm_done_m0

; DI void phase_rwkv_prep(const Params& p, char* lds) {
;     ...
;     for (int u = blockIdx.x; u < NUNIT; u += gridDim.x) {
;         int tid = threadIdx.x; asm volatile("" : "+v"(tid));
;         const int lane = tid & 63, wave = __builtin_amdgcn_readfirstlane(tid >> 6); const int qm = wave >> 1, qn = wave & 1; const int r = lane & 31, h5 = lane >> 5;
;         int b, h, c, row0, ntok; bool prm = u < 2048;
;         if (prm) { b = u >> 10; h = (u >> 7) & 7; c = u & 127; row0 = b * 8192 + c * 64; ntok = 64; }
;         else { const int s = u - 2048; b = s >> 3; h = s & 7; c = 0; row0 = NTP + b * 16; ntok = 16; }
;         const int mode0 = prm ? (c > 0 ? 0 : 1) : 2;
.Llt_skip:
	s_mov_b32 s4, 0
	s_bitcmp1_b32 s33, 7
	s_cbranch_scc1 .Llt_nopoll
	s_and_b32 s3, s33, 0x7f
	s_cmp_ge_u32 s3, 0x7e
	s_cselect_b32 s4, 1, 0
.Llt_nopoll:
	v_writelane_b32 v237, s4, 6
	s_mov_b32 s101, 0
	s_add_u32 s0, s78, 0x1800
	s_addc_u32 s1, s79, 0
	v_writelane_b32 v236, s0, 18
	s_mov_b32 s9, 0
	v_mov_b32_e32 v71, 0
	v_writelane_b32 v236, s1, 19
	s_add_u32 s0, s78, 0x1900
	s_addc_u32 s1, s79, 0
	v_writelane_b32 v236, s0, 20
	s_movk_i32 s7, 0x2100
	s_mov_b32 s99, 0xbfb8aa3b
	v_writelane_b32 v236, s1, 21
	s_add_u32 s0, s54, 0x2b40000
	s_addc_u32 s1, s55, 0
	v_writelane_b32 v236, s0, 22
	s_mov_b32 s88, 0x800000
	s_mov_b32 s89, 0x3f317217
	v_writelane_b32 v236, s1, 23
	s_add_u32 s0, s54, 0x2b50000
	s_addc_u32 s1, s55, 0
	v_writelane_b32 v236, s0, 24
	s_mov_b32 s38, 0x7f800000
	v_mov_b32_e32 v73, 0x41b17218
	v_writelane_b32 v236, s1, 25
	s_add_u32 s0, s54, 0xfc18000
	v_writelane_b32 v236, s0, 26
	s_addc_u32 s0, s55, 0
	v_writelane_b32 v236, s0, 27
	s_add_u32 s0, s54, 0xb414800
	v_writelane_b32 v236, s0, 28
	s_addc_u32 s0, s55, 0
	v_writelane_b32 v236, s0, 29
	s_add_u32 s0, s54, 0xd814800
	v_writelane_b32 v236, s0, 30
	s_addc_u32 s0, s55, 0
	v_writelane_b32 v236, s0, 31
	s_add_u32 s0, s54, 0xc614800
	v_writelane_b32 v236, s0, 32
	s_addc_u32 s0, s55, 0
	v_writelane_b32 v236, s0, 33
	s_add_i32 s0, 0, 0x12000
	s_mov_b32 s90, s33
	s_and_b32 s2, s33, 0x7f
	s_lshr_b32 s3, s33, 8
	s_lshl_b32 s3, s3, 7
	s_or_b32 s2, s2, s3
	s_addk_i32 s2, 0x800
	s_bitcmp0_b32 s33, 7
	s_cselect_b32 s90, s33, s2
	v_writelane_b32 v236, s0, 34
	s_branch .LBB0_199
.LBB0_198:
	s_or_b64 exec, exec, s[0:1]
	s_add_i32 s101, s101, 1
	v_readlane_b32 s2, v236, 3
	s_bitcmp0_b32 s2, 7
	s_cselect_b32 s4, 4, 5
	s_cselect_b32 s3, 0, 1
	s_sub_i32 s3, s101, s3
	s_lshl_b32 s3, s3, 9
	s_add_i32 s90, s2, s3
	s_cmp_lt_u32 s101, s4
	s_cselect_b32 s90, s90, 0x7fff
	s_mov_b32 s4, 0
	s_cmpk_ge_i32 s90, 0x800
	s_cbranch_scc1 .Lp2_nopoll
	s_and_b32 s3, s90, 0x7f
	s_cmp_ge_u32 s3, 0x7e
	s_cselect_b32 s4, 1, 0
	s_cmpk_ge_i32 s90, 0x400
	s_cselect_b32 s4, 1, s4
.Lp2_nopoll:
	v_writelane_b32 v237, s4, 6
	s_cmpk_lt_i32 s90, 0x900
	s_barrier
	s_cbranch_scc0 .LBB0_315

; DI unsigned pack2(float lo, float hi) { f32x2_t v = {lo, hi}; bf16x2_t b = __builtin_convertvector(v, bf16x2_t); return __builtin_bit_cast(unsigned, b); }
; DI void phase_rwkv_prep(const Params& p, char* lds) {
;     ...
;             for (int g = 0; g < 4; g += 2) {
;                 unsigned ax = pack2(aY[4 * g], aY[4 * g + 1]), ay = pack2(aY[4 * g + 2], aY[4 * g + 3]), bx = pack2(aY[4 * g + 4], aY[4 * g + 5]), by = pack2(aY[4 * g + 6], aY[4 * g + 7]);
;                 { auto rr = __builtin_amdgcn_permlane32_swap(ax, bx, false, false); ax = rr[0]; bx = rr[1]; }
;                 { auto rr = __builtin_amdgcn_permlane32_swap(ay, by, false, false); ay = rr[0]; by = rr[1]; }
;                 if (n < ntok) *(uint4*)((u16*)(p.ws + W_XB) + (size_t)(row0 + n) * DM + 512 + h * 64 + 32 * qm + 8 * g + 8 * h5) = (uint4){ax, ay, bx, by};
;             }
.LBB0_307:
	v_readlane_b32 s0, v237, 6
	v_readlane_b32 s5, v237, 7
	s_andn2_b32 s0, s0, s5
	s_cmp_eq_u32 s0, 0
	s_cbranch_scc1 .Lpl_end_x
	s_add_u32 s96, s54, 0xfc14808
	s_addc_u32 s97, s55, 0
	v_mov_b32_e32 v240, 0
	s_mov_b32 s5, 0
.Lpl_x:
	global_load_dword v241, v240, s[96:97] sc1
	s_waitcnt vmcnt(0)
	v_readfirstlane_b32 s0, v241
	s_cmp_ge_u32 s0, 0x104
	s_cbranch_scc1 .Lpl_ok_x
	s_sleep 2
	s_add_i32 s5, s5, 1
	s_cmp_lt_u32 s5, 0x10000
	s_cbranch_scc1 .Lpl_x
.Lpl_ok_x:
	v_writelane_b32 v237, 1, 7
